# conv_layer gain-folding loops: 8 gain + 8 weight loads per iteration issued together behind counted waits (original serial loop kept for a null gain pointer)
# speedup vs baseline: 1.0138x; 1.0090x over previous
; #define LAS __attribute__((address_space(3)))
; __device__ __forceinline__ void conv_item(const float* W, int Nsrc, int K, int k0, int scol, bf16_t* WT, int drow, const float* gain, float cscale, LAS float* scr, int lane) {
; #pragma unroll 8
;     for (int i = 0; i < 32; ++i) { const int kk = 2 * i + (lane >> 5); const float gg = gain ? gain[k0 + kk] * cscale : cscale;
;         scr[kk * 33 + (lane & 31)] = W[(size_t)(k0 + kk) * Nsrc + scol + (lane & 31)] * gg; }
;     asm volatile("s_waitcnt lgkmcnt(0)" ::: "memory");
; __device__ __forceinline__ void conv_layer(const Args& a, int l, bf16_t* WB, LAS unsigned char* lds, int ngw) {
;     ...
;         if (r < I4) { const int gi = r / 512, rr = r % 512, kb = rr / 32, db = rr % 32;
;             conv_item(a.w_gate + ((size_t)l * 3 + gi) * 1024 * 1024, 1024, 1024, kb * 64, db * 32, WB + WO_WG, gi * 1024 + db * 32, a.norm_mix + l * 1024, 1.f, scr, lane);
;             continue; }
.LBB0_34:
	s_andn2_b64 vcc, exec, s[0:1]
	s_cbranch_vccnz .LBB0_54
	s_lshr_b32 s0, s13, 9
	v_readlane_b32 s22, v255, 32
	v_readlane_b32 s23, v255, 33
	s_add_u32 s0, s22, s0
	s_addc_u32 s1, s23, 0
	s_lshl_b32 s15, s14, 2
	s_lshl_b64 s[0:1], s[0:1], 22
	s_and_b32 s15, s15, 0xf80
	s_or_b32 s0, s0, s15
	s_bfe_u32 s15, s27, 0x40006
	s_lshl_b32 s16, s15, 6
	v_or_b32_e32 v0, s16, v51
	v_lshl_or_b32 v42, v0, 12, s0
	v_mov_b32_e32 v43, s1
	v_or_b32_e32 v0, s16, v52
	v_lshl_add_u64 v[26:27], v[18:19], 0, v[42:43]
	v_lshl_or_b32 v42, v0, 12, s0
	v_or_b32_e32 v0, s16, v53
	v_lshl_add_u64 v[30:31], v[18:19], 0, v[42:43]
	v_lshl_or_b32 v42, v0, 12, s0
	v_or_b32_e32 v0, s16, v54
	v_lshl_add_u64 v[32:33], v[18:19], 0, v[42:43]
	v_lshl_or_b32 v42, v0, 12, s0
	v_or_b32_e32 v0, s16, v55
	v_lshl_add_u64 v[34:35], v[18:19], 0, v[42:43]
	v_lshl_or_b32 v42, v0, 12, s0
	v_or_b32_e32 v0, s16, v56
	v_lshl_add_u64 v[36:37], v[18:19], 0, v[42:43]
	v_lshl_or_b32 v42, v0, 12, s0
	v_or_b32_e32 v0, s16, v57
	v_lshl_add_u64 v[38:39], v[18:19], 0, v[42:43]
	v_lshl_or_b32 v42, v0, 12, s0
	v_lshl_add_u64 v[40:41], v[18:19], 0, v[42:43]
	v_or_b32_e32 v42, s16, v2
	v_lshlrev_b32_e32 v0, 2, v42
	v_lshl_or_b32 v42, v42, 12, s0
	v_readlane_b32 s28, v255, 9
	v_lshl_or_b32 v28, s15, 8, v20
	v_mov_b32_e32 v29, v5
	v_lshl_add_u64 v[42:43], v[18:19], 0, v[42:43]
	s_mov_b64 s[0:1], 0
	v_readlane_b32 s29, v255, 10
	v_mov_b32_e32 v46, v50
	s_andn2_b64 vcc, exec, s[24:25]
	s_cbranch_vccnz .LBB0_37
.Lcv37_loop:
	v_lshl_add_u64 v[110:111], s[28:29], 0, v[0:1]
	v_lshl_add_u64 v[112:113], s[28:29], 0, v[28:29]
	global_load_dword v120, v[110:111], off offset:-56
	global_load_dword v121, v[112:113], off offset:-48
	global_load_dword v122, v[112:113], off offset:-40
	global_load_dword v123, v[112:113], off offset:-32
	global_load_dword v124, v[112:113], off offset:-24
	global_load_dword v125, v[112:113], off offset:-16
	global_load_dword v126, v[112:113], off offset:-8
	global_load_dword v127, v[112:113], off
	v_lshl_add_u64 v[130:131], v[42:43], 0, s[0:1]
	v_lshl_add_u64 v[132:133], v[40:41], 0, s[0:1]
	v_lshl_add_u64 v[134:135], v[38:39], 0, s[0:1]
	v_lshl_add_u64 v[136:137], v[36:37], 0, s[0:1]
	v_lshl_add_u64 v[138:139], v[34:35], 0, s[0:1]
	v_lshl_add_u64 v[140:141], v[32:33], 0, s[0:1]
	v_lshl_add_u64 v[142:143], v[30:31], 0, s[0:1]
	v_lshl_add_u64 v[144:145], v[26:27], 0, s[0:1]
	global_load_dword v150, v[130:131], off
	global_load_dword v151, v[132:133], off
	global_load_dword v152, v[134:135], off
	global_load_dword v153, v[136:137], off
	global_load_dword v154, v[138:139], off
	global_load_dword v155, v[140:141], off
	global_load_dword v156, v[142:143], off
	global_load_dword v157, v[144:145], off
	s_waitcnt vmcnt(7)
	v_mul_f32_e32 v120, v120, v150
	ds_write_b32 v46, v120
	s_waitcnt vmcnt(6)
	v_mul_f32_e32 v121, v121, v151
	ds_write_b32 v46, v121 offset:264
	s_waitcnt vmcnt(5)
	v_mul_f32_e32 v122, v122, v152
	ds_write_b32 v46, v122 offset:528
	s_waitcnt vmcnt(4)
	v_mul_f32_e32 v123, v123, v153
	ds_write_b32 v46, v123 offset:792
	s_waitcnt vmcnt(3)
	v_mul_f32_e32 v124, v124, v154
	ds_write_b32 v46, v124 offset:1056
	s_waitcnt vmcnt(2)
	v_mul_f32_e32 v125, v125, v155
	ds_write_b32 v46, v125 offset:1320
	s_waitcnt vmcnt(1)
	v_mul_f32_e32 v126, v126, v156
	ds_write_b32 v46, v126 offset:1584
	s_waitcnt vmcnt(0)
	v_mul_f32_e32 v127, v127, v157
	ds_write_b32 v46, v127 offset:1848
	s_add_u32 s0, s0, 0x10000
	s_addc_u32 s1, s1, 0
	s_add_u32 s28, s28, 64
	s_addc_u32 s29, s29, 0
	v_add_u32_e32 v46, 0x840, v46
	s_cmp_lg_u32 s0, 0x40000
	s_cbranch_scc1 .Lcv37_loop
	s_branch .LBB0_53

; #define LAS __attribute__((address_space(3)))
; __device__ __forceinline__ void conv_item(const float* W, int Nsrc, int K, int k0, int scol, bf16_t* WT, int drow, const float* gain, float cscale, LAS float* scr, int lane) {
; #pragma unroll 8
;     for (int i = 0; i < 32; ++i) { const int kk = 2 * i + (lane >> 5); const float gg = gain ? gain[k0 + kk] * cscale : cscale;
;         scr[kk * 33 + (lane & 31)] = W[(size_t)(k0 + kk) * Nsrc + scol + (lane & 31)] * gg; }
;     asm volatile("s_waitcnt lgkmcnt(0)" ::: "memory");
; __device__ __forceinline__ void conv_layer(const Args& a, int l, bf16_t* WB, LAS unsigned char* lds, int ngw) {
;     ...
;         if (r < I3) { const int kb = r / 120, db = r % 120, col = db * 32;
;             const bool isq = col < 512 || (col >= 1536 && col < 2048) || (col >= 3072 && col < 3584);
;             conv_item(a.w_in + (size_t)l * 1024 * INC, INC, 1024, kb * 64, col, WB + WO_WIN, col, a.norm_mix + l * 1024, isq ? 0.125f * LOG2E : 1.f, scr, lane);
;             continue; }
.LBB0_55:
	s_andn2_b64 vcc, exec, s[0:1]
	s_cbranch_vccnz .LBB0_75
	s_add_i32 s0, s12, 0xef80
	s_and_b32 s26, s0, 0xffff
	s_mul_i32 s1, s26, 0x8889
	s_lshr_b32 s16, s1, 16
	s_lshr_b32 s1, s1, 22
	s_mulk_i32 s1, 0x78
	s_sub_i32 s28, s0, s1
	s_and_b32 s31, s28, 0xffff
	s_lshl_b32 s15, s31, 5
	s_cmp_lt_u32 s31, 16
	s_cselect_b64 s[0:1], -1, 0
	s_and_b32 s35, s28, 0x70
	s_cmp_eq_u32 s35, 48
	s_cselect_b64 s[28:29], -1, 0
	s_cmpk_eq_i32 s35, 0x60
	s_cselect_b64 s[38:39], -1, 0
	s_or_b64 s[28:29], s[28:29], s[38:39]
	v_mov_b32_e32 v0, 0x3e38aa3b
	s_or_b64 vcc, s[28:29], s[0:1]
	s_and_b32 s16, s16, 0xffc0
	v_cndmask_b32_e32 v46, 1.0, v0, vcc
	v_or_b32_e32 v0, s16, v51
	s_lshl_b32 s80, s31, 7
	v_mul_u32_u24_e32 v0, 0x3c00, v0
	v_lshl_add_u64 v[26:27], s[80:81], 0, v[0:1]
	v_or_b32_e32 v0, s16, v52
	v_mul_u32_u24_e32 v0, 0x3c00, v0
	v_lshl_add_u64 v[30:31], s[80:81], 0, v[0:1]
	v_or_b32_e32 v0, s16, v53
	v_mul_u32_u24_e32 v0, 0x3c00, v0
	v_lshl_add_u64 v[32:33], s[80:81], 0, v[0:1]
	v_or_b32_e32 v0, s16, v54
	v_mul_u32_u24_e32 v0, 0x3c00, v0
	v_lshl_add_u64 v[34:35], s[80:81], 0, v[0:1]
	v_or_b32_e32 v0, s16, v55
	v_mul_u32_u24_e32 v0, 0x3c00, v0
	v_lshl_add_u64 v[36:37], s[80:81], 0, v[0:1]
	v_or_b32_e32 v0, s16, v56
	v_mul_u32_u24_e32 v0, 0x3c00, v0
	s_mul_hi_u32 s0, s26, 0x2222223
	v_lshl_add_u64 v[38:39], s[80:81], 0, v[0:1]
	v_or_b32_e32 v0, s16, v57
	v_lshl_or_b32 v28, s0, 8, v20
	v_mul_u32_u24_e32 v0, 0x3c00, v0
	v_or_b32_e32 v44, s16, v2
	v_mov_b64_e32 v[42:43], s[80:81]
	s_movk_i32 s0, 0x3c00
	v_lshl_add_u64 v[40:41], s[80:81], 0, v[0:1]
	v_mad_u64_u32 v[42:43], s[0:1], v44, s0, v[42:43]
	v_readlane_b32 s28, v255, 9
	v_lshl_add_u64 v[26:27], v[22:23], 0, v[26:27]
	v_mov_b32_e32 v29, v5
	v_lshl_add_u64 v[30:31], v[22:23], 0, v[30:31]
	v_lshl_add_u64 v[32:33], v[22:23], 0, v[32:33]
	v_lshl_add_u64 v[34:35], v[22:23], 0, v[34:35]
	v_lshl_add_u64 v[36:37], v[22:23], 0, v[36:37]
	v_lshl_add_u64 v[38:39], v[22:23], 0, v[38:39]
	v_lshl_add_u64 v[40:41], v[22:23], 0, v[40:41]
	v_lshlrev_b32_e32 v0, 2, v44
	v_lshl_add_u64 v[42:43], v[22:23], 0, v[42:43]
	s_mov_b64 s[0:1], 0
	v_readlane_b32 s29, v255, 10
	v_mov_b32_e32 v47, v50
	s_andn2_b64 vcc, exec, s[24:25]
	s_cbranch_vccnz .LBB0_58
.Lcv58_loop:
	v_lshl_add_u64 v[110:111], s[28:29], 0, v[0:1]
	v_lshl_add_u64 v[112:113], s[28:29], 0, v[28:29]
	global_load_dword v120, v[110:111], off offset:-56
	global_load_dword v121, v[112:113], off offset:-48
	global_load_dword v122, v[112:113], off offset:-40
	global_load_dword v123, v[112:113], off offset:-32
	global_load_dword v124, v[112:113], off offset:-24
	global_load_dword v125, v[112:113], off offset:-16
	global_load_dword v126, v[112:113], off offset:-8
	global_load_dword v127, v[112:113], off
	v_lshl_add_u64 v[130:131], v[42:43], 0, s[0:1]
	v_lshl_add_u64 v[132:133], v[40:41], 0, s[0:1]
	v_lshl_add_u64 v[134:135], v[38:39], 0, s[0:1]
	v_lshl_add_u64 v[136:137], v[36:37], 0, s[0:1]
	v_lshl_add_u64 v[138:139], v[34:35], 0, s[0:1]
	v_lshl_add_u64 v[140:141], v[32:33], 0, s[0:1]
	v_lshl_add_u64 v[142:143], v[30:31], 0, s[0:1]
	v_lshl_add_u64 v[144:145], v[26:27], 0, s[0:1]
	global_load_dword v150, v[130:131], off
	global_load_dword v151, v[132:133], off
	global_load_dword v152, v[134:135], off
	global_load_dword v153, v[136:137], off
	global_load_dword v154, v[138:139], off
	global_load_dword v155, v[140:141], off
	global_load_dword v156, v[142:143], off
	global_load_dword v157, v[144:145], off
	s_waitcnt vmcnt(7)
	v_mul_f32_e32 v120, v46, v120
	v_mul_f32_e32 v120, v120, v150
	ds_write_b32 v47, v120
	s_waitcnt vmcnt(6)
	v_mul_f32_e32 v121, v46, v121
	v_mul_f32_e32 v121, v121, v151
	ds_write_b32 v47, v121 offset:264
	s_waitcnt vmcnt(5)
	v_mul_f32_e32 v122, v46, v122
	v_mul_f32_e32 v122, v122, v152
	ds_write_b32 v47, v122 offset:528
	s_waitcnt vmcnt(4)
	v_mul_f32_e32 v123, v46, v123
	v_mul_f32_e32 v123, v123, v153
	ds_write_b32 v47, v123 offset:792
	s_waitcnt vmcnt(3)
	v_mul_f32_e32 v124, v46, v124
	v_mul_f32_e32 v124, v124, v154
	ds_write_b32 v47, v124 offset:1056
	s_waitcnt vmcnt(2)
	v_mul_f32_e32 v125, v46, v125
	v_mul_f32_e32 v125, v125, v155
	ds_write_b32 v47, v125 offset:1320
	s_waitcnt vmcnt(1)
	v_mul_f32_e32 v126, v46, v126
	v_mul_f32_e32 v126, v126, v156
	ds_write_b32 v47, v126 offset:1584
	s_waitcnt vmcnt(0)
	v_mul_f32_e32 v127, v46, v127
	v_mul_f32_e32 v127, v127, v157
	ds_write_b32 v47, v127 offset:1848
	s_add_u32 s0, s0, 0x3c000
	s_addc_u32 s1, s1, 0
	s_add_u32 s28, s28, 64
	s_addc_u32 s29, s29, 0
	v_add_u32_e32 v47, 0x840, v47
	s_cmp_lg_u32 s0, 0xf0000
	s_cbranch_scc1 .Lcv58_loop
	s_branch .LBB0_74

; #define LAS __attribute__((address_space(3)))
; __device__ __forceinline__ void conv_item(const float* W, int Nsrc, int K, int k0, int scol, bf16_t* WT, int drow, const float* gain, float cscale, LAS float* scr, int lane) {
; #pragma unroll 8
;     for (int i = 0; i < 32; ++i) { const int kk = 2 * i + (lane >> 5); const float gg = gain ? gain[k0 + kk] * cscale : cscale;
;         scr[kk * 33 + (lane & 31)] = W[(size_t)(k0 + kk) * Nsrc + scol + (lane & 31)] * gg; }
;     asm volatile("s_waitcnt lgkmcnt(0)" ::: "memory");
; __device__ __forceinline__ void conv_layer(const Args& a, int l, bf16_t* WB, LAS unsigned char* lds, int ngw) {
;     ...
;         if (r < I1 || (r >= I1 + I2 + I3 + I4 + I5 + I6 && r < I1 + I2 + I3 + I4 + I5 + I6 + I1)) {
;             const bool second = r >= I1; if (second) r -= I1 + I2 + I3 + I4 + I5 + I6;
;             const int kb = r / 176, db = r % 176, pn = db >> 3, o8 = db & 7; const int scol = (o8 >> 2) * DFF + 128 * pn + (o8 & 3) * 32;
;             conv_item((second ? a.w_ffn2_in : a.w_ffn1_in) + (size_t)l * 1024 * 5632, 5632, 1024, kb * 64, scol, WB + (second ? WO_W3 : WO_W1), db * 32, (second ? a.norm_ffn2 : a.norm_ffn1) + l * 1024, 1.f, scr, lane);
;             continue; }
.LBB0_81:
	s_andn2_b64 vcc, exec, s[0:1]
	s_cbranch_vccnz .LBB0_20
	s_cmpk_gt_i32 s12, 0xaff
	s_cselect_b64 s[0:1], -1, 0
	s_and_b64 s[28:29], s[0:1], exec
	s_cselect_b32 s15, s34, s12
	v_readlane_b32 s52, v254, 46
	s_mul_hi_i32 s16, s15, 0x2e8ba2e9
	v_readlane_b32 s56, v254, 50
	v_readlane_b32 s57, v254, 51
	v_readlane_b32 s58, v254, 52
	v_readlane_b32 s59, v254, 53
	s_cselect_b32 s38, s58, s76
	s_cselect_b32 s39, s59, s77
	s_cselect_b32 s40, s56, s74
	s_cselect_b32 s41, s57, s75
	s_lshr_b32 s26, s16, 31
	s_ashr_i32 s16, s16, 5
	s_add_i32 s16, s16, s26
	s_mul_i32 s26, s16, 0xb0
	s_sub_i32 s15, s15, s26
	s_bfe_i32 s26, s15, 0x10002
	s_lshl_b32 s28, s15, 4
	s_lshl_b32 s15, s15, 5
	s_and_b32 s26, s26, 0xb00
	s_and_b32 s42, s28, 0xffffff80
	s_and_b32 s43, s15, 0x60
	s_lshl_b32 s28, s16, 6
	s_cmp_lg_u64 s[40:41], 0
	s_cselect_b64 s[34:35], -1, 0
	s_add_i32 s26, s26, s42
	v_lshl_add_u64 v[46:47], s[38:39], 0, v[24:25]
	s_or_b32 s38, s26, s43
	s_ashr_i32 s39, s38, 31
	s_lshl_b64 s[38:39], s[38:39], 2
	v_or_b32_e32 v0, s28, v51
	v_mov_b64_e32 v[58:59], s[38:39]
	s_movk_i32 s16, 0x5800
	v_mad_i64_i32 v[26:27], s[38:39], v0, s16, v[58:59]
	v_or_b32_e32 v0, s28, v52
	v_mad_i64_i32 v[30:31], s[38:39], v0, s16, v[58:59]
	v_or_b32_e32 v0, s28, v53
	v_mad_i64_i32 v[32:33], s[38:39], v0, s16, v[58:59]
	v_or_b32_e32 v0, s28, v54
	s_ashr_i32 s29, s28, 31
	v_mad_i64_i32 v[34:35], s[38:39], v0, s16, v[58:59]
	v_or_b32_e32 v0, s28, v55
	v_mov_b32_e32 v45, s29
	v_or_b32_e32 v44, s28, v2
	v_mad_i64_i32 v[36:37], s[38:39], v0, s16, v[58:59]
	v_or_b32_e32 v0, s28, v56
	v_lshlrev_b64 v[28:29], 2, v[44:45]
	v_readlane_b32 s22, v255, 30
	v_mad_i64_i32 v[38:39], s[38:39], v0, s16, v[58:59]
	v_or_b32_e32 v0, s28, v57
	v_ashrrev_i32_e32 v45, 31, v44
	v_readlane_b32 s23, v255, 31
	s_add_u32 s40, s40, s22
	v_mad_i64_i32 v[40:41], s[38:39], v0, s16, v[58:59]
	v_lshlrev_b64 v[42:43], 2, v[44:45]
	v_mad_i64_i32 v[44:45], s[38:39], v44, s16, v[58:59]
	s_mov_b64 s[30:31], 0
	v_lshl_add_u64 v[26:27], v[46:47], 0, v[26:27]
	s_addc_u32 s41, s41, s23
	v_lshl_add_u64 v[30:31], v[46:47], 0, v[30:31]
	v_lshl_add_u64 v[32:33], v[46:47], 0, v[32:33]
	v_lshl_add_u64 v[34:35], v[46:47], 0, v[34:35]
	v_lshl_add_u64 v[36:37], v[46:47], 0, v[36:37]
	v_lshl_add_u64 v[38:39], v[46:47], 0, v[38:39]
	v_lshl_add_u64 v[40:41], v[46:47], 0, v[40:41]
	v_lshl_add_u64 v[44:45], v[46:47], 0, v[44:45]
	v_mov_b32_e32 v0, v50
	v_readlane_b32 s53, v254, 47
	v_readlane_b32 s54, v254, 48
	v_readlane_b32 s55, v254, 49
	v_readlane_b32 s60, v254, 54
	v_readlane_b32 s61, v254, 55
	v_readlane_b32 s62, v254, 56
	v_readlane_b32 s63, v254, 57
	v_readlane_b32 s64, v254, 58
	v_readlane_b32 s65, v254, 59
	v_readlane_b32 s66, v254, 60
	v_readlane_b32 s67, v254, 61
	s_andn2_b64 vcc, exec, s[34:35]
	s_cbranch_vccnz .LBB0_84
.Lcv84_loop:
	v_lshl_add_u64 v[110:111], s[40:41], 0, v[42:43]
	v_lshl_add_u64 v[112:113], s[40:41], 0, v[28:29]
	global_load_dword v120, v[110:111], off offset:-56
	global_load_dword v121, v[112:113], off offset:-48
	global_load_dword v122, v[112:113], off offset:-40
	global_load_dword v123, v[112:113], off offset:-32
	global_load_dword v124, v[112:113], off offset:-24
	global_load_dword v125, v[112:113], off offset:-16
	global_load_dword v126, v[112:113], off offset:-8
	global_load_dword v127, v[112:113], off
	v_lshl_add_u64 v[130:131], v[44:45], 0, s[30:31]
	v_lshl_add_u64 v[132:133], v[40:41], 0, s[30:31]
	v_lshl_add_u64 v[134:135], v[38:39], 0, s[30:31]
	v_lshl_add_u64 v[136:137], v[36:37], 0, s[30:31]
	v_lshl_add_u64 v[138:139], v[34:35], 0, s[30:31]
	v_lshl_add_u64 v[140:141], v[32:33], 0, s[30:31]
	v_lshl_add_u64 v[142:143], v[30:31], 0, s[30:31]
	v_lshl_add_u64 v[144:145], v[26:27], 0, s[30:31]
	global_load_dword v150, v[130:131], off
	global_load_dword v151, v[132:133], off
	global_load_dword v152, v[134:135], off
	global_load_dword v153, v[136:137], off
	global_load_dword v154, v[138:139], off
	global_load_dword v155, v[140:141], off
	global_load_dword v156, v[142:143], off
	global_load_dword v157, v[144:145], off
	s_waitcnt vmcnt(7)
	v_mul_f32_e32 v120, v120, v150
	ds_write_b32 v0, v120
	s_waitcnt vmcnt(6)
	v_mul_f32_e32 v121, v121, v151
	ds_write_b32 v0, v121 offset:264
	s_waitcnt vmcnt(5)
	v_mul_f32_e32 v122, v122, v152
	ds_write_b32 v0, v122 offset:528
	s_waitcnt vmcnt(4)
	v_mul_f32_e32 v123, v123, v153
	ds_write_b32 v0, v123 offset:792
	s_waitcnt vmcnt(3)
	v_mul_f32_e32 v124, v124, v154
	ds_write_b32 v0, v124 offset:1056
	s_waitcnt vmcnt(2)
	v_mul_f32_e32 v125, v125, v155
	ds_write_b32 v0, v125 offset:1320
	s_waitcnt vmcnt(1)
	v_mul_f32_e32 v126, v126, v156
	ds_write_b32 v0, v126 offset:1584
	s_waitcnt vmcnt(0)
	v_mul_f32_e32 v127, v127, v157
	ds_write_b32 v0, v127 offset:1848
	s_add_u32 s30, s30, 0x58000
	s_addc_u32 s31, s31, 0
	s_add_u32 s40, s40, 64
	s_addc_u32 s41, s41, 0
	v_add_u32_e32 v0, 0x840, v0
	s_cmp_lg_u32 s30, 0x160000
	s_cbranch_scc1 .Lcv84_loop
	s_branch .LBB0_19
